# running-max subtraction folded into the QK MFMA chain (extra bf16 k-step, max kept bf16-exact), rare path out of line; rescale test on uniform keep flag; deferred cross-half row-sum; misc wait/nop tri
# speedup vs baseline: 1.0061x; 1.0061x over previous
; __device__ __forceinline__ int v_rd_base(int lane) { return ((lane & 3) << 3) | (((lane >> 2) & 3) << 6) | (((lane >> 4) & 1) << 5) | (((lane >> 5) & 1) << 8); }
; #define DMA_K(k0, s) do { DMA_KN(k0, s); DMA_KR(k0, s); } while (0)
; #define DMA_V(k0, off) do { const char* vb_ = (const char*)Vh + (size_t)(k0) * (LDV * 2); \
;     GLDS(vb_ + v_off[0], V_lds + (off) + (wid * 2) * 1024); GLDS(vb_ + v_off[1], V_lds + (off) + (wid * 2 + 1) * 1024); } while (0)
; __device__ __forceinline__ void attn_unit(const bf16_t* __restrict__ Qb, const bf16_t* __restrict__ KNh, const bf16_t* __restrict__ KRs, const bf16_t* __restrict__ Vh,
;                                           bf16_t* __restrict__ Ob, float* __restrict__ ssa, int seq, char* lds) {
;   const int tid = threadIdx.x, wid = __builtin_amdgcn_readfirstlane(tid >> 6), lane = tid & 63, r32 = lane & 31, hi = lane >> 5;
;   char* V_lds = lds + OFF_V; char* KN_lds = lds + OFF_KN; char* KR_lds = lds + OFF_KR;
;   float* ws = (float*)(lds + OFF_WS) + wid * 64; float* li_l = ws; float* al_l = ws + 32;
;   float m_reg = -1e30f, l_reg = 0; f32x16 o[4] = {}; bf16x8 qr[12];
;   const bf16_t* Qw = Qb + (long)(wid * QBLK + r32) * LDQ + hi * 8;
; #pragma unroll
;   for (int d0 = 0; d0 < 12; ++d0) qr[d0] = *reinterpret_cast<const bf16x8*>(Qw + d0 * 16);
;   const int vb0 = (int)(uintptr_t)V_lds + v_rd_base(lane);
;   unsigned kn_off[2], v_off[2], kr_off;
; #pragma unroll
;   for (int i = 0; i < 2; ++i) {
;     const int q = (wid * 2 + i) * 64 + lane;
;     { const int row = q >> 4, c = (q & 15) ^ (row & 15); kn_off[i] = (unsigned)(row * LDKN * 2 + c * 16); }
;     { const int sub = q >> 5, kk = (sub >> 2) * 8 + ((q & 31) >> 2), cc = (sub & 3) * 32 + (q & 3) * 8, k = (kk & ~0xC) | ((kk & 4) << 1) | ((kk & 8) >> 1);
;       v_off[i] = (unsigned)(k * LDV * 2 + cc * 2); }
;   }
;   { const int q = wid * 64 + lane, row = q >> 3, c = (q & 7) ^ ((row >> 1) & 7); kr_off = (unsigned)(row * LDKR * 2 + c * 16); }
;   typedef __attribute__((address_space(3))) unsigned lds_u32;
;     ...
;   f32x16 p0, p1; float al0, al1; bf16x8 pa0, pa1, pa2, pa3; const int NT = seq / KVBLK;
;     ...
;   DMA_K(0, 0); DMA_V(0, 0);
;   asm volatile("s_waitcnt vmcnt(0)" ::: "memory"); __syncthreads();
.LBB0_516:
	s_ashr_i32 s59, s58, 31
	s_mul_i32 s61, s58, 0x900
	s_mul_hi_i32 s60, s58, 0x900
	s_add_u32 s63, s13, s61
	s_addc_u32 s65, s14, s60
	s_mul_i32 s60, s16, 0xc0
	s_ashr_i32 s61, s60, 31
	s_lshl_b64 s[60:61], s[60:61], 1
	s_add_u32 s64, s63, s60
	s_addc_u32 s65, s65, s61
	s_ashr_i32 s63, s62, 31
	s_mul_i32 s92, s62, 0x600
	s_mul_hi_i32 s90, s62, 0x600
	s_add_u32 s66, s15, s92
	s_addc_u32 s67, s22, s90
	s_lshl_b32 s60, s16, 7
	s_ashr_i32 s61, s60, 31
	s_lshl_b64 s[60:61], s[60:61], 1
	s_add_u32 s66, s66, s60
	s_addc_u32 s67, s67, s61
	s_add_u32 s18, s66, 0x18000
	s_addc_u32 s19, s67, 0
	s_lshl_b64 s[62:63], s[62:63], 7
	s_add_u32 s86, s23, s62
	s_addc_u32 s87, s28, s63
	s_add_u32 s20, s86, 0x2000
	s_addc_u32 s21, s87, 0
	s_add_u32 s16, s29, s92
	s_addc_u32 s80, s30, s90
	s_add_u32 s88, s16, s60
	v_readfirstlane_b32 s16, v146
	s_addc_u32 s89, s80, s61
	s_add_u32 s34, s88, 0x18000
	s_addc_u32 s35, s89, 0
	s_lshr_b32 s80, s16, 6
	s_and_b32 s93, s16, 0xffffffc0
	s_lshl_b32 s16, s80, 5
	v_or_b32_e32 v0, s16, v148
	v_mov_b64_e32 v[2:3], s[64:65]
	v_mad_u64_u32 v[2:3], s[64:65], v0, s75, v[2:3]
	v_lshl_add_u64 v[2:3], v[2:3], 0, v[150:151]
	s_lshl_b32 s64, s80, 7
	global_load_dwordx4 v[98:101], v[2:3], off
	global_load_dwordx4 v[102:105], v[2:3], off offset:32
	global_load_dwordx4 v[106:109], v[2:3], off offset:64
	global_load_dwordx4 v[110:113], v[2:3], off offset:96
	global_load_dwordx4 v[114:117], v[2:3], off offset:128
	global_load_dwordx4 v[118:121], v[2:3], off offset:160
	global_load_dwordx4 v[122:125], v[2:3], off offset:192
	global_load_dwordx4 v[126:129], v[2:3], off offset:224
	global_load_dwordx4 v[130:133], v[2:3], off offset:256
	global_load_dwordx4 v[134:137], v[2:3], off offset:288
	global_load_dwordx4 v[138:141], v[2:3], off offset:320
	global_load_dwordx4 v[142:145], v[2:3], off offset:352
	v_or_b32_e32 v2, s64, v147
	s_ashr_i32 s64, s64, 4
	s_and_b32 s94, s64, -16
	s_lshr_b32 s64, s64, 1
	s_and_b32 s95, s64, 4
	v_or_b32_e32 v0, s94, v173
	v_or_b32_e32 v0, s95, v0
	v_mul_lo_u32 v3, v0, s74
	v_ashrrev_i32_e32 v0, 4, v2
	v_xor_b32_e32 v4, v0, v146
	v_or_b32_e32 v5, 64, v2
	s_movk_i32 s64, 0x60
	v_mul_lo_u32 v0, v0, s74
	v_lshlrev_b32_e32 v4, 4, v4
	v_ashrrev_i32_e32 v2, 4, v5
	v_and_or_b32 v5, v5, s64, v172
	v_and_or_b32 v0, v4, s73, v0
	v_or_b32_e32 v4, v3, v174
	v_lshl_or_b32 v3, v5, 1, v3
	v_or_b32_e32 v5, s93, v147
	s_movk_i32 s64, 0x70
	v_bitop3_b32 v7, v5, s64, v149 bitop3:0x48
	s_lshl_b32 s64, s80, 11
	s_add_i32 s81, s64, 0
	v_xor_b32_e32 v6, v2, v146
	s_add_i32 s82, s81, 0x8000
	v_mul_lo_u32 v2, v2, s74
	v_lshlrev_b32_e32 v6, 4, v6
	s_mov_b32 m0, s82
	s_add_i32 s83, s81, 0x8400
	v_and_or_b32 v2, v6, s73, v2
	global_load_lds_dwordx4 v0, s[66:67]
	s_mov_b32 m0, s83
	v_lshlrev_b32_e32 v6, 4, v5
	global_load_lds_dwordx4 v2, s[66:67]
	s_lshl_b32 s66, s80, 10
	s_add_i32 s84, s66, 0
	s_add_i32 s85, s84, 0x10000
	v_and_or_b32 v5, v6, s76, v7
	s_mov_b32 m0, s85
	s_lshl_b32 s64, s93, 2
	global_load_lds_dwordx4 v5, s[86:87]
	s_mov_b32 m0, s81
	s_add_i32 s86, s81, 0x400
	global_load_lds_dwordx4 v4, s[88:89]
	s_mov_b32 m0, s86
	s_add_i32 s80, s64, 0
	global_load_lds_dwordx4 v3, s[88:89]
	v_mov_b32_e32 v152, v0
	v_mov_b32_e32 v153, v2
	v_mov_b32_e32 v154, v5
	v_mov_b32_e32 v155, v4
	v_mov_b32_e32 v156, v3
	v_add_u32_e32 v157, 0x10000, v177
	v_add_u32_e32 v158, 0x10000, v178
	v_add_u32_e32 v159, 0x10000, v179
	v_add_u32_e32 v160, 0x10000, v180
	s_add_i32 s80, s80, 0x14000
	s_add_u32 s64, s92, s60
	s_addc_u32 s65, s90, s61
	s_or_b32 s67, s95, s94
	v_add_u32_e32 v4, s67, v173
	v_mul_lo_u32 v6, v4, s74
	v_or_b32_e32 v4, v184, v6
	v_mov_b32_e32 v5, v1
	v_or3_b32 v4, v183, v6, v186
	v_or_b32_e32 v4, s66, v185
	v_mov_b32_e32 v3, v1
	v_and_or_b32 v4, v4, s76, v7
	v_mov_b32_e32 v14, v1
	v_mov_b32_e32 v15, v1
	s_waitcnt vmcnt(0)
	v_mov_b32_e32 v0, v1
	v_mov_b32_e32 v2, v1
	v_mov_b32_e32 v4, v1
	v_mov_b32_e32 v6, v1
	v_mov_b32_e32 v7, v1
	v_mov_b32_e32 v8, v1
	v_mov_b32_e32 v9, v1
	v_mov_b32_e32 v10, v1
	v_mov_b32_e32 v11, v1
	v_mov_b32_e32 v12, v1
	v_mov_b32_e32 v13, v1
	v_mov_b64_e32 v[64:65], v[14:15]
	v_mov_b64_e32 v[48:49], v[14:15]
	v_mov_b64_e32 v[32:33], v[14:15]
	v_mov_b64_e32 v[62:63], v[12:13]
	v_mov_b64_e32 v[60:61], v[10:11]
	v_mov_b64_e32 v[58:59], v[8:9]
	v_mov_b64_e32 v[56:57], v[6:7]
	v_mov_b64_e32 v[54:55], v[4:5]
	v_mov_b64_e32 v[52:53], v[2:3]
	v_mov_b64_e32 v[50:51], v[0:1]
	v_mov_b64_e32 v[46:47], v[12:13]
	v_mov_b64_e32 v[44:45], v[10:11]
	v_mov_b64_e32 v[42:43], v[8:9]
	v_mov_b64_e32 v[40:41], v[6:7]
	v_mov_b64_e32 v[38:39], v[4:5]
	v_mov_b64_e32 v[36:37], v[2:3]
	v_mov_b64_e32 v[34:35], v[0:1]
	v_mov_b64_e32 v[30:31], v[12:13]
	v_mov_b64_e32 v[28:29], v[10:11]
	v_mov_b64_e32 v[26:27], v[8:9]
	v_mov_b64_e32 v[24:25], v[6:7]
	v_mov_b64_e32 v[22:23], v[4:5]
	v_mov_b64_e32 v[20:21], v[2:3]
	v_mov_b64_e32 v[18:19], v[0:1]
	v_mov_b64_e32 v[16:17], v[14:15]
	s_mov_b32 s87, 2
	v_lshl_add_u32 v196, v148, 2, s80
	v_mov_b32_e32 v161, 0xf149f2ca
	s_mov_b32 s99, 0xff800000
	v_mov_b32_e32 v250, 0
	v_mov_b32_e32 v251, 0
	v_mov_b32_e32 v253, 0x3f80
	v_mov_b32_e32 v254, 0
	v_mov_b32_e32 v255, 0
	v_mbcnt_lo_u32_b32 v252, -1, 0
	v_mbcnt_hi_u32_b32 v252, -1, v252
	v_cmp_gt_u32_e32 vcc, 32, v252
	s_nop 1
	v_cndmask_b32_e32 v252, 0, v253, vcc
	v_mov_b32_e32 v253, 0
	v_mov_b32_e32 v197, 0
	v_mov_b64_e32 v[14:15], v[12:13]
	v_mov_b64_e32 v[12:13], v[10:11]
	v_mov_b64_e32 v[10:11], v[8:9]
	v_mov_b64_e32 v[8:9], v[6:7]
	v_mov_b64_e32 v[6:7], v[4:5]
	v_mov_b64_e32 v[4:5], v[2:3]
	v_mov_b64_e32 v[2:3], v[0:1]
	s_waitcnt vmcnt(0) lgkmcnt(0)
	s_barrier
	s_branch .LBB0_519

; #define VWAIT(N, f) asm volatile("s_waitcnt lgkmcnt(" #N ")" : "+v"(f.l0), "+v"(f.h0), "+v"(f.l1), "+v"(f.h1) :: "memory")
; template <int H> __device__ __forceinline__ void pv_half(f32x16* o, int vb, bf16x8 paL, bf16x8 paH) {
;   VFrag fa = pv_rd<H, 0>(vb), fb = pv_rd<H, 1>(vb);
;   VWAIT(4, fa); pv_mma(o[0], fa, paL, paH);
;   fa = pv_rd<H, 2>(vb);
;   VWAIT(4, fb); pv_mma(o[1], fb, paL, paH);
;   fb = pv_rd<H, 3>(vb);
;   VWAIT(4, fa); pv_mma(o[2], fa, paL, paH);
;   VWAIT(0, fb); pv_mma(o[3], fb, paL, paH);
; }
.LBB0_518:
	v_fma_f32 v76, v197, v0, v198
	v_fma_f32 v0, v76, v200, v201
	v_fma_f32 v76, v0, v249, v91
	v_fma_f32 v197, v76, v93, v74
	ds_read_b64_tr_b16 v[74:75], v181 offset:0x2000
	ds_read_b64_tr_b16 v[76:77], v181 offset:0x2800
	ds_read_b64_tr_b16 v[78:79], v181 offset:0x3000
	ds_read_b64_tr_b16 v[80:81], v181 offset:0x3800
	ds_read_b64_tr_b16 v[82:83], v181 offset:0x2200
	ds_read_b64_tr_b16 v[84:85], v181 offset:0x2a00
	ds_read_b64_tr_b16 v[86:87], v181 offset:0x3200
	ds_read_b64_tr_b16 v[88:89], v181 offset:0x3a00
	s_waitcnt lgkmcnt(4)
	v_mfma_f32_32x32x16_bf16 v[50:65], v[66:69], v[74:77], v[50:65]
	ds_read_b64_tr_b16 v[74:75], v181 offset:0x2400
	ds_read_b64_tr_b16 v[76:77], v181 offset:0x2c00
	s_add_i32 s87, s87, 2
	s_and_b64 vcc, exec, s[62:63]
	v_mfma_f32_32x32x16_bf16 v[50:65], v[70:73], v[78:81], v[50:65]
	ds_read_b64_tr_b16 v[78:79], v181 offset:0x3400
	ds_read_b64_tr_b16 v[80:81], v181 offset:0x3c00
	s_waitcnt lgkmcnt(4)
	v_mfma_f32_32x32x16_bf16 v[34:49], v[66:69], v[82:85], v[34:49]
	ds_read_b64_tr_b16 v[82:83], v181 offset:0x2600
	ds_read_b64_tr_b16 v[84:85], v181 offset:0x2e00
	v_mfma_f32_32x32x16_bf16 v[34:49], v[70:73], v[86:89], v[34:49]
	ds_read_b64_tr_b16 v[86:87], v181 offset:0x3600
	ds_read_b64_tr_b16 v[88:89], v181 offset:0x3e00
	s_waitcnt vmcnt(0) lgkmcnt(0)
	v_mfma_f32_32x32x16_bf16 v[18:33], v[66:69], v[74:77], v[18:33]
	s_barrier
	v_mfma_f32_32x32x16_bf16 v[2:17], v[66:69], v[82:85], v[2:17]
	v_mfma_f32_32x32x16_bf16 v[18:33], v[70:73], v[78:81], v[18:33]
	v_mfma_f32_32x32x16_bf16 v[2:17], v[70:73], v[86:89], v[2:17]
	s_cbranch_vccnz .LBB0_542

; __device__ __forceinline__ void sm_half(f32x16& p, float& m_reg, float& l_reg, float& alpha, bf16x8& paL, bf16x8& paH) {
;   float a = fmaxf(fmaxf(p[0], p[1]), p[2]), b = fmaxf(fmaxf(p[3], p[4]), p[5]);
;   a = fmaxf(fmaxf(a, p[6]), p[7]); b = fmaxf(fmaxf(b, p[8]), p[9]); a = fmaxf(fmaxf(a, p[10]), p[11]); b = fmaxf(fmaxf(b, p[12]), p[13]); a = fmaxf(fmaxf(a, p[14]), p[15]);
;   float pmax = fmaxf(a, b);
;   { auto rr = __builtin_amdgcn_permlane32_swap(__float_as_uint(pmax), __float_as_uint(pmax), false, false);
;     pmax = fmaxf(__uint_as_float(rr[0]), __uint_as_float(rr[1])); }
;   const bool keep = __all(pmax - m_reg <= THRL);
;   const float mn = keep ? m_reg : fmaxf(m_reg, pmax);
;   alpha = __builtin_amdgcn_exp2f(m_reg - mn); m_reg = mn;
; #pragma unroll
;   for (int r = 0; r < 16; ++r) p[r] = __builtin_amdgcn_exp2f(p[r] - mn);
;   float ps = 0;
; #pragma unroll
;   for (int r = 0; r < 16; ++r) ps += p[r];
;   { auto rr = __builtin_amdgcn_permlane32_swap(__float_as_uint(ps), __float_as_uint(ps), false, false);
;     ps = __uint_as_float(rr[0]) + __uint_as_float(rr[1]); }
;   l_reg = l_reg * alpha + ps;
;     ...
;   PK4(p, 0, paL); PK4(p, 8, paH);
;     ...
; }
; template <int H> __device__ __forceinline__ void qkt_half(f32x16& p, const char* Kn, const char* Kr, const bf16x8* qr, int r32, int hi) {
;   p = f32x16{};
; #pragma unroll
;   for (int d0 = 0; d0 < 8; ++d0) { const int cb = (d0 * 16 + hi * 8) * 2;
;     const bf16x8 f = *reinterpret_cast<const bf16x8*>(Kn + KSWZ(32 * H + r32, cb)); p = __builtin_amdgcn_mfma_f32_32x32x16_bf16(f, qr[d0], p, 0, 0, 0); }
; #pragma unroll
;   for (int d0 = 0; d0 < 4; ++d0) { const int cb = (d0 * 16 + hi * 8) * 2;
;     const bf16x8 f = *reinterpret_cast<const bf16x8*>(Kr + KRSWZ(32 * H + r32, cb)); p = __builtin_amdgcn_mfma_f32_32x32x16_bf16(f, qr[8 + d0], p, 0, 0, 0); }
; }
.LBB0_521:
	ds_read_b128 v[66:69], v187 offset:32768
	ds_read_b128 v[70:73], v188 offset:32768
	ds_read_b128 v[74:77], v189 offset:32768
	ds_read_b128 v[78:81], v190 offset:32768
	v_mfma_f32_32x32x16_bf16 v[82:97], v[250:253], v[252:255], 0
	s_waitcnt lgkmcnt(3)
	v_mfma_f32_32x32x16_bf16 v[82:97], v[66:69], v[98:101], v[82:97]
	ds_read_b128 v[66:69], v191 offset:32768
	s_waitcnt lgkmcnt(3)
	v_mfma_f32_32x32x16_bf16 v[82:97], v[70:73], v[102:105], v[82:97]
	ds_read_b128 v[70:73], v192 offset:32768
	s_waitcnt lgkmcnt(3)
	v_mfma_f32_32x32x16_bf16 v[82:97], v[74:77], v[106:109], v[82:97]
	ds_read_b128 v[74:77], v193 offset:32768
	s_waitcnt lgkmcnt(3)
	v_mfma_f32_32x32x16_bf16 v[82:97], v[78:81], v[110:113], v[82:97]
	ds_read_b128 v[78:81], v194 offset:32768
	s_waitcnt lgkmcnt(3)
	v_mfma_f32_32x32x16_bf16 v[82:97], v[66:69], v[114:117], v[82:97]
	ds_read_b128 v[66:69], v157
	s_waitcnt lgkmcnt(3)
	v_mfma_f32_32x32x16_bf16 v[82:97], v[70:73], v[118:121], v[82:97]
	ds_read_b128 v[70:73], v158
	s_waitcnt lgkmcnt(3)
	v_mfma_f32_32x32x16_bf16 v[82:97], v[74:77], v[122:125], v[82:97]
	ds_read_b128 v[74:77], v159
	s_waitcnt lgkmcnt(3)
	v_mfma_f32_32x32x16_bf16 v[82:97], v[78:81], v[126:129], v[82:97]
	ds_read_b128 v[78:81], v160
	s_waitcnt lgkmcnt(3)
	v_mfma_f32_32x32x16_bf16 v[82:97], v[66:69], v[130:133], v[82:97]
	ds_read_b128 v[66:69], v187 offset:40960
	ds_read_b128 v[168:171], v188 offset:40960
	s_waitcnt lgkmcnt(4)
	v_mfma_f32_32x32x16_bf16 v[82:97], v[70:73], v[134:137], v[82:97]
	ds_read_b128 v[198:201], v189 offset:40960
	ds_read_b128 v[202:205], v190 offset:40960
	s_waitcnt lgkmcnt(5)
	v_mfma_f32_32x32x16_bf16 v[82:97], v[74:77], v[138:141], v[82:97]
	ds_read_b128 v[206:209], v191 offset:40960
	ds_read_b128 v[210:213], v192 offset:40960
	s_waitcnt lgkmcnt(6)
	v_mfma_f32_32x32x16_bf16 v[82:97], v[78:81], v[142:145], v[82:97]
	ds_read_b128 v[214:217], v193 offset:40960
	ds_read_b128 v[218:221], v194 offset:40960
	s_nop 3
	s_waitcnt lgkmcnt(2)
	v_mfma_f32_32x32x16_bf16 v[66:81], v[66:69], v[98:101], 0
	ds_read_b128 v[222:225], v157 offset:4096
	ds_read_b128 v[226:229], v158 offset:4096
	ds_read_b128 v[230:233], v159 offset:4096
	ds_read_b128 v[234:237], v160 offset:4096
	v_max_f32_e32 v0, v82, v83
	v_max3_f32 v238, v85, v86, v87
	v_max3_f32 v0, v0, v84, v88
	v_max3_f32 v165, v238, v90, v91
	v_mfma_f32_32x32x16_bf16 v[66:81], v[168:171], v[102:105], v[66:81]
	v_max3_f32 v0, v0, v89, v92
	v_max3_f32 v165, v165, v94, v95
	v_max3_f32 v0, v0, v93, v96
	v_max3_f32 v0, v0, v97, v165
	v_mov_b32_e32 v165, v0
	s_nop 1
	v_permlane32_swap_b32_e32 v0, v165
	v_mfma_f32_32x32x16_bf16 v[66:81], v[198:201], v[106:109], v[66:81]
	v_max_f32_e32 v0, v0, v165
	v_cmp_ge_f32_e32 vcc, s99, v0
	s_cmp_eq_u64 vcc, exec
	s_cbranch_scc0 .Lrare_00
	v_mov_b32_e32 v0, 1.0
.Lcont_00:
	v_mfma_f32_32x32x16_bf16 v[66:81], v[202:205], v[110:113], v[66:81]
	v_exp_f32_e32 v82, v82
	v_mfma_f32_32x32x16_bf16 v[66:81], v[206:209], v[114:117], v[66:81]
	v_exp_f32_e32 v83, v83
	v_exp_f32_e32 v84, v84
	v_exp_f32_e32 v85, v85
	v_mfma_f32_32x32x16_bf16 v[66:81], v[210:213], v[118:121], v[66:81]
	v_exp_f32_e32 v86, v86
	v_exp_f32_e32 v87, v87
	v_add_f32_e32 v164, v83, v82
	v_exp_f32_e32 v88, v88
	s_waitcnt lgkmcnt(4)
	v_mfma_f32_32x32x16_bf16 v[66:81], v[214:217], v[122:125], v[66:81]
	v_add_f32_e32 v164, v84, v164
	v_exp_f32_e32 v89, v89
	v_add_f32_e32 v164, v85, v164
	v_exp_f32_e32 v90, v90
	v_add_f32_e32 v164, v86, v164
	v_mfma_f32_32x32x16_bf16 v[66:81], v[218:221], v[126:129], v[66:81]
	v_exp_f32_e32 v91, v91
	v_add_f32_e32 v164, v87, v164
	v_exp_f32_e32 v92, v92
	v_add_f32_e32 v164, v88, v164
	s_waitcnt lgkmcnt(0)
	v_mfma_f32_32x32x16_bf16 v[66:81], v[222:225], v[130:133], v[66:81]
	v_exp_f32_e32 v93, v93
	v_add_f32_e32 v164, v89, v164
	v_exp_f32_e32 v94, v94
	v_add_f32_e32 v164, v90, v164
	v_exp_f32_e32 v95, v95
	v_mfma_f32_32x32x16_bf16 v[66:81], v[226:229], v[134:137], v[66:81]
	v_add_f32_e32 v164, v91, v164
	v_exp_f32_e32 v96, v96
	v_add_f32_e32 v164, v92, v164
	v_exp_f32_e32 v97, v97
	v_add_f32_e32 v164, v93, v164
	v_add_f32_e32 v164, v94, v164
	v_mfma_f32_32x32x16_bf16 v[66:81], v[230:233], v[138:141], v[66:81]
	v_add_f32_e32 v164, v95, v164
	v_add_f32_e32 v164, v96, v164
	v_add_f32_e32 v198, v97, v164
	v_cvt_pk_bf16_f32 v82, v82, v83
	v_cvt_pk_bf16_f32 v83, v84, v85
	v_mfma_f32_32x32x16_bf16 v[66:81], v[234:237], v[142:145], v[66:81]
	v_mfma_f32_32x32x16_bf16 v[66:81], v[250:253], v[252:255], v[66:81]
	v_cvt_pk_bf16_f32 v84, v86, v87
	v_cvt_pk_bf16_f32 v85, v88, v89
	v_cvt_pk_bf16_f32 v86, v90, v91
	v_cvt_pk_bf16_f32 v87, v92, v93
	v_cvt_pk_bf16_f32 v88, v94, v95
	v_cvt_pk_bf16_f32 v89, v96, v97
	s_nop 0
	v_permlane32_swap_b32_e32 v82, v84
	v_permlane32_swap_b32_e32 v83, v85
	v_permlane32_swap_b32_e32 v86, v88
	v_permlane32_swap_b32_e32 v87, v89
	s_cbranch_scc1 .LBB0_525
	s_and_saveexec_b64 s[64:65], s[0:1]
	ds_write_b32 v196, v0 offset:128
	s_or_b64 exec, exec, s[64:65]
	s_waitcnt lgkmcnt(0)
	v_add_u32_e32 v164, s80, v176
	ds_read_b128 v[90:93], v164 offset:224
	ds_read_b128 v[94:97], v164 offset:192
	ds_read_b128 v[168:171], v164 offset:160
	ds_read_b128 v[202:205], v164 offset:128
	s_waitcnt lgkmcnt(0)
	v_pk_mul_f32 v[62:63], v[62:63], v[90:91]
	v_pk_mul_f32 v[58:59], v[58:59], v[94:95]
	v_pk_mul_f32 v[54:55], v[54:55], v[168:169]
	v_pk_mul_f32 v[64:65], v[64:65], v[92:93]
	v_pk_mul_f32 v[60:61], v[60:61], v[96:97]
	v_pk_mul_f32 v[56:57], v[56:57], v[170:171]
	v_pk_mul_f32 v[52:53], v[52:53], v[204:205]
	v_pk_mul_f32 v[50:51], v[50:51], v[202:203]
	v_pk_mul_f32 v[46:47], v[46:47], v[90:91]
	v_pk_mul_f32 v[42:43], v[42:43], v[94:95]
	v_pk_mul_f32 v[38:39], v[38:39], v[168:169]
	v_pk_mul_f32 v[48:49], v[48:49], v[92:93]
	v_pk_mul_f32 v[44:45], v[44:45], v[96:97]
	v_pk_mul_f32 v[40:41], v[40:41], v[170:171]
	v_pk_mul_f32 v[36:37], v[36:37], v[204:205]
	v_pk_mul_f32 v[34:35], v[34:35], v[202:203]
	v_pk_mul_f32 v[30:31], v[30:31], v[90:91]
	v_pk_mul_f32 v[26:27], v[26:27], v[94:95]
	v_pk_mul_f32 v[22:23], v[22:23], v[168:169]
	v_pk_mul_f32 v[32:33], v[32:33], v[92:93]
	v_pk_mul_f32 v[28:29], v[28:29], v[96:97]
	v_pk_mul_f32 v[24:25], v[24:25], v[170:171]
	v_pk_mul_f32 v[20:21], v[20:21], v[204:205]
	v_pk_mul_f32 v[18:19], v[18:19], v[202:203]
	v_pk_mul_f32 v[14:15], v[14:15], v[90:91]
	v_pk_mul_f32 v[10:11], v[10:11], v[94:95]
	v_pk_mul_f32 v[6:7], v[6:7], v[168:169]
	v_pk_mul_f32 v[16:17], v[16:17], v[92:93]
	v_pk_mul_f32 v[12:13], v[12:13], v[96:97]
	v_pk_mul_f32 v[8:9], v[8:9], v[170:171]
	v_pk_mul_f32 v[4:5], v[4:5], v[204:205]
	v_pk_mul_f32 v[2:3], v[2:3], v[202:203]

; #define VWAIT(N, f) asm volatile("s_waitcnt lgkmcnt(" #N ")" : "+v"(f.l0), "+v"(f.h0), "+v"(f.l1), "+v"(f.h1) :: "memory")
; __device__ __forceinline__ void sm_half(f32x16& p, float& m_reg, float& l_reg, float& alpha, bf16x8& paL, bf16x8& paH) {
;   float a = fmaxf(fmaxf(p[0], p[1]), p[2]), b = fmaxf(fmaxf(p[3], p[4]), p[5]);
;   a = fmaxf(fmaxf(a, p[6]), p[7]); b = fmaxf(fmaxf(b, p[8]), p[9]); a = fmaxf(fmaxf(a, p[10]), p[11]); b = fmaxf(fmaxf(b, p[12]), p[13]); a = fmaxf(fmaxf(a, p[14]), p[15]);
;   float pmax = fmaxf(a, b);
;   { auto rr = __builtin_amdgcn_permlane32_swap(__float_as_uint(pmax), __float_as_uint(pmax), false, false);
;     pmax = fmaxf(__uint_as_float(rr[0]), __uint_as_float(rr[1])); }
;   const bool keep = __all(pmax - m_reg <= THRL);
;   const float mn = keep ? m_reg : fmaxf(m_reg, pmax);
;   alpha = __builtin_amdgcn_exp2f(m_reg - mn); m_reg = mn;
; #pragma unroll
;   for (int r = 0; r < 16; ++r) p[r] = __builtin_amdgcn_exp2f(p[r] - mn);
;   float ps = 0;
; #pragma unroll
;   for (int r = 0; r < 16; ++r) ps += p[r];
;   { auto rr = __builtin_amdgcn_permlane32_swap(__float_as_uint(ps), __float_as_uint(ps), false, false);
;     ps = __uint_as_float(rr[0]) + __uint_as_float(rr[1]); }
;   l_reg = l_reg * alpha + ps;
;     ...
;   PK4(p, 0, paL); PK4(p, 8, paH);
; template <int H, int D0> __device__ __forceinline__ VFrag pv_rd(int vb) {
;   VFrag f; f.l0 = tr_read<v_rd_off(D0, 2 * H, 0)>(vb); f.h0 = tr_read<v_rd_off(D0, 2 * H, 1)>(vb); f.l1 = tr_read<v_rd_off(D0, 2 * H + 1, 0)>(vb); f.h1 = tr_read<v_rd_off(D0, 2 * H + 1, 1)>(vb); return f;
; }
; __device__ __forceinline__ void pv_mma(f32x16& od, VFrag& f, bf16x8 paL, bf16x8 paH) {
;     ...
;   od = __builtin_amdgcn_mfma_f32_32x32x16_bf16(paL, PK(f.l0, f.h0), od, 0, 0, 0);
;   od = __builtin_amdgcn_mfma_f32_32x32x16_bf16(paH, PK(f.l1, f.h1), od, 0, 0, 0);
;     ...
; }
; template <int H> __device__ __forceinline__ void pv_half(f32x16* o, int vb, bf16x8 paL, bf16x8 paH) {
;   VFrag fa = pv_rd<H, 0>(vb), fb = pv_rd<H, 1>(vb);
;   VWAIT(4, fa); pv_mma(o[0], fa, paL, paH);
;   fa = pv_rd<H, 2>(vb);
;   VWAIT(4, fb); pv_mma(o[1], fb, paL, paH);
;   fb = pv_rd<H, 3>(vb);
;   VWAIT(4, fa); pv_mma(o[2], fa, paL, paH);
;   VWAIT(0, fb); pv_mma(o[3], fb, paL, paH);
; }
.LBB0_527:
	ds_read_b64_tr_b16 v[90:91], v175 offset:0
	ds_read_b64_tr_b16 v[92:93], v175 offset:0x800
	ds_read_b64_tr_b16 v[94:95], v175 offset:0x1000
	ds_read_b64_tr_b16 v[96:97], v175 offset:0x1800
	ds_read_b64_tr_b16 v[202:203], v175 offset:0x200
	ds_read_b64_tr_b16 v[204:205], v175 offset:0xa00
	ds_read_b64_tr_b16 v[206:207], v175 offset:0x1200
	ds_read_b64_tr_b16 v[208:209], v175 offset:0x1a00
	s_waitcnt lgkmcnt(4)
	v_mfma_f32_32x32x16_bf16 v[50:65], v[82:85], v[90:93], v[50:65]
	ds_read_b64_tr_b16 v[90:91], v175 offset:0x400
	ds_read_b64_tr_b16 v[92:93], v175 offset:0xc00
	ds_read_b64_tr_b16 v[210:211], v175 offset:0x1400
	ds_read_b64_tr_b16 v[212:213], v175 offset:0x1c00
	s_waitcnt lgkmcnt(4)
	ds_read_b64_tr_b16 v[214:215], v175 offset:0x600
	ds_read_b64_tr_b16 v[216:217], v175 offset:0xe00
	v_mfma_f32_32x32x16_bf16 v[50:65], v[86:89], v[94:97], v[50:65]
	ds_read_b64_tr_b16 v[94:95], v175 offset:0x1600
	ds_read_b64_tr_b16 v[96:97], v175 offset:0x1e00
	s_waitcnt lgkmcnt(4)
	s_waitcnt lgkmcnt(0)
	v_mfma_f32_32x32x16_bf16 v[34:49], v[82:85], v[202:205], v[34:49]
	v_max_f32_e32 v201, v66, v67
	v_max3_f32 v202, v69, v70, v71
	v_max3_f32 v201, v201, v68, v72
	v_max3_f32 v202, v202, v74, v75
	v_max3_f32 v201, v201, v73, v76
	v_max3_f32 v202, v202, v78, v79
	v_max3_f32 v201, v201, v77, v80
	v_max3_f32 v201, v201, v81, v202
	v_mov_b32_e32 v202, v201
	s_nop 1
	v_permlane32_swap_b32_e32 v201, v202
	v_mfma_f32_32x32x16_bf16 v[18:33], v[82:85], v[90:93], v[18:33]
	v_max_f32_e32 v90, v201, v202
	v_cmp_ge_f32_e32 vcc, s99, v90
	s_cmp_eq_u64 vcc, exec
	s_cbranch_scc0 .Lrare_01
	v_mov_b32_e32 v200, 1.0
.Lcont_01:
	v_exp_f32_e32 v66, v66
	v_exp_f32_e32 v67, v67
	v_exp_f32_e32 v68, v68
	v_exp_f32_e32 v69, v69
	v_mfma_f32_32x32x16_bf16 v[2:17], v[82:85], v[214:217], v[2:17]
	v_exp_f32_e32 v70, v70
	v_exp_f32_e32 v71, v71
	v_add_f32_e32 v82, v67, v66
	v_exp_f32_e32 v72, v72
	v_add_f32_e32 v82, v68, v82
	v_exp_f32_e32 v73, v73
	v_add_f32_e32 v82, v69, v82
	v_exp_f32_e32 v74, v74
	v_add_f32_e32 v82, v70, v82
	v_exp_f32_e32 v75, v75
	v_add_f32_e32 v82, v71, v82
	v_exp_f32_e32 v76, v76
	v_add_f32_e32 v82, v72, v82
	v_exp_f32_e32 v77, v77
	v_add_f32_e32 v82, v73, v82
	v_exp_f32_e32 v78, v78
	v_add_f32_e32 v82, v74, v82
	v_exp_f32_e32 v79, v79
	v_add_f32_e32 v82, v75, v82
	v_mfma_f32_32x32x16_bf16 v[34:49], v[86:89], v[206:209], v[34:49]
	v_exp_f32_e32 v80, v80
	v_add_f32_e32 v82, v76, v82
	v_exp_f32_e32 v81, v81
	v_add_f32_e32 v82, v77, v82
	v_add_f32_e32 v82, v78, v82
	v_mfma_f32_32x32x16_bf16 v[18:33], v[86:89], v[210:213], v[18:33]
	v_add_f32_e32 v82, v79, v82
	v_add_f32_e32 v82, v80, v82
	v_add_f32_e32 v201, v81, v82
	v_cvt_pk_bf16_f32 v66, v66, v67
	v_cvt_pk_bf16_f32 v67, v68, v69
	v_mfma_f32_32x32x16_bf16 v[2:17], v[86:89], v[94:97], v[2:17]
	v_cvt_pk_bf16_f32 v68, v70, v71
	v_cvt_pk_bf16_f32 v69, v72, v73
	v_cvt_pk_bf16_f32 v70, v74, v75
	v_cvt_pk_bf16_f32 v71, v76, v77
	v_cvt_pk_bf16_f32 v72, v78, v79
	v_cvt_pk_bf16_f32 v73, v80, v81
	s_nop 0
	v_permlane32_swap_b32_e32 v66, v68
	v_permlane32_swap_b32_e32 v67, v69
	v_permlane32_swap_b32_e32 v70, v72
	v_permlane32_swap_b32_e32 v71, v73
	s_cbranch_scc1 .LBB0_531
	s_and_saveexec_b64 s[62:63], s[0:1]
	ds_write_b32 v196, v200 offset:128
	s_or_b64 exec, exec, s[62:63]
	s_waitcnt lgkmcnt(0)
	v_add_u32_e32 v86, s80, v176
	ds_read_b128 v[74:77], v86 offset:224
	ds_read_b128 v[78:81], v86 offset:192
	ds_read_b128 v[82:85], v86 offset:160
	ds_read_b128 v[86:89], v86 offset:128
	s_waitcnt lgkmcnt(0)
	v_pk_mul_f32 v[62:63], v[62:63], v[74:75]
	v_pk_mul_f32 v[58:59], v[58:59], v[78:79]
	v_pk_mul_f32 v[54:55], v[54:55], v[82:83]
	v_pk_mul_f32 v[64:65], v[64:65], v[76:77]
	v_pk_mul_f32 v[60:61], v[60:61], v[80:81]
	v_pk_mul_f32 v[56:57], v[56:57], v[84:85]
	v_pk_mul_f32 v[52:53], v[52:53], v[88:89]
	v_pk_mul_f32 v[50:51], v[50:51], v[86:87]
	v_pk_mul_f32 v[46:47], v[46:47], v[74:75]
	v_pk_mul_f32 v[42:43], v[42:43], v[78:79]
	v_pk_mul_f32 v[38:39], v[38:39], v[82:83]
	v_pk_mul_f32 v[48:49], v[48:49], v[76:77]
	v_pk_mul_f32 v[44:45], v[44:45], v[80:81]
	v_pk_mul_f32 v[40:41], v[40:41], v[84:85]
	v_pk_mul_f32 v[36:37], v[36:37], v[88:89]
	v_pk_mul_f32 v[34:35], v[34:35], v[86:87]
	v_pk_mul_f32 v[30:31], v[30:31], v[74:75]
	v_pk_mul_f32 v[26:27], v[26:27], v[78:79]
	v_pk_mul_f32 v[22:23], v[22:23], v[82:83]
	v_pk_mul_f32 v[32:33], v[32:33], v[76:77]
	v_pk_mul_f32 v[28:29], v[28:29], v[80:81]
	v_pk_mul_f32 v[24:25], v[24:25], v[84:85]
	v_pk_mul_f32 v[20:21], v[20:21], v[88:89]
	v_pk_mul_f32 v[18:19], v[18:19], v[86:87]
	v_pk_mul_f32 v[14:15], v[14:15], v[74:75]
	v_pk_mul_f32 v[10:11], v[10:11], v[78:79]
	v_pk_mul_f32 v[6:7], v[6:7], v[82:83]
	v_pk_mul_f32 v[16:17], v[16:17], v[76:77]
	v_pk_mul_f32 v[12:13], v[12:13], v[80:81]
	v_pk_mul_f32 v[8:9], v[8:9], v[84:85]
	v_pk_mul_f32 v[4:5], v[4:5], v[88:89]
	v_pk_mul_f32 v[2:3], v[2:3], v[86:87]
; #define VWAIT(N, f) asm volatile("s_waitcnt lgkmcnt(" #N ")" : "+v"(f.l0), "+v"(f.h0), "+v"(f.l1), "+v"(f.h1) :: "memory")
; template <int H> __device__ __forceinline__ void qkt_half(f32x16& p, const char* Kn, const char* Kr, const bf16x8* qr, int r32, int hi) {
;   p = f32x16{};
; #pragma unroll
;   for (int d0 = 0; d0 < 8; ++d0) { const int cb = (d0 * 16 + hi * 8) * 2;
;     const bf16x8 f = *reinterpret_cast<const bf16x8*>(Kn + KSWZ(32 * H + r32, cb)); p = __builtin_amdgcn_mfma_f32_32x32x16_bf16(f, qr[d0], p, 0, 0, 0); }
; #pragma unroll
;   for (int d0 = 0; d0 < 4; ++d0) { const int cb = (d0 * 16 + hi * 8) * 2;
;     const bf16x8 f = *reinterpret_cast<const bf16x8*>(Kr + KRSWZ(32 * H + r32, cb)); p = __builtin_amdgcn_mfma_f32_32x32x16_bf16(f, qr[8 + d0], p, 0, 0, 0); }
; }
; template <int H, int D0> __device__ __forceinline__ VFrag pv_rd(int vb) {
;   VFrag f; f.l0 = tr_read<v_rd_off(D0, 2 * H, 0)>(vb); f.h0 = tr_read<v_rd_off(D0, 2 * H, 1)>(vb); f.l1 = tr_read<v_rd_off(D0, 2 * H + 1, 0)>(vb); f.h1 = tr_read<v_rd_off(D0, 2 * H + 1, 1)>(vb); return f;
; }
; __device__ __forceinline__ void pv_mma(f32x16& od, VFrag& f, bf16x8 paL, bf16x8 paH) {
;     ...
;   od = __builtin_amdgcn_mfma_f32_32x32x16_bf16(paL, PK(f.l0, f.h0), od, 0, 0, 0);
;   od = __builtin_amdgcn_mfma_f32_32x32x16_bf16(paH, PK(f.l1, f.h1), od, 0, 0, 0);
;     ...
; }
; template <int H> __device__ __forceinline__ void pv_half(f32x16* o, int vb, bf16x8 paL, bf16x8 paH) {
;   VFrag fa = pv_rd<H, 0>(vb), fb = pv_rd<H, 1>(vb);
;   VWAIT(4, fa); pv_mma(o[0], fa, paL, paH);
;   fa = pv_rd<H, 2>(vb);
;   VWAIT(4, fb); pv_mma(o[1], fb, paL, paH);
;   fb = pv_rd<H, 3>(vb);
;   VWAIT(4, fa); pv_mma(o[2], fa, paL, paH);
;   VWAIT(0, fb); pv_mma(o[3], fb, paL, paH);
; }
.LBB0_531:
	ds_read_b64_tr_b16 v[74:75], v175 offset:0x2000
	ds_read_b64_tr_b16 v[76:77], v175 offset:0x2800
	ds_read_b64_tr_b16 v[78:79], v175 offset:0x3000
	ds_read_b64_tr_b16 v[80:81], v175 offset:0x3800
	ds_read_b64_tr_b16 v[82:83], v175 offset:0x2200
	ds_read_b64_tr_b16 v[84:85], v175 offset:0x2a00
	ds_read_b64_tr_b16 v[86:87], v175 offset:0x3200
	ds_read_b64_tr_b16 v[88:89], v175 offset:0x3a00
	s_cmp_lt_u32 s87, s79
	s_waitcnt lgkmcnt(4)
	s_cselect_b64 s[64:65], -1, 0
	v_mfma_f32_32x32x16_bf16 v[50:65], v[66:69], v[74:77], v[50:65]
	ds_read_b64_tr_b16 v[74:75], v175 offset:0x2400
	ds_read_b64_tr_b16 v[76:77], v175 offset:0x2c00
	s_cmp_ge_u32 s87, s79
	s_cselect_b64 s[62:63], -1, 0
	s_and_b64 vcc, exec, s[62:63]
	v_mfma_f32_32x32x16_bf16 v[50:65], v[70:73], v[78:81], v[50:65]
	ds_read_b64_tr_b16 v[78:79], v175 offset:0x3400
	ds_read_b64_tr_b16 v[80:81], v175 offset:0x3c00
	s_waitcnt lgkmcnt(4)
	v_mfma_f32_32x32x16_bf16 v[34:49], v[66:69], v[82:85], v[34:49]
	ds_read_b64_tr_b16 v[82:83], v175 offset:0x2600
	ds_read_b64_tr_b16 v[84:85], v175 offset:0x2e00
	v_mfma_f32_32x32x16_bf16 v[34:49], v[70:73], v[86:89], v[34:49]
	ds_read_b64_tr_b16 v[86:87], v175 offset:0x3600
	ds_read_b64_tr_b16 v[88:89], v175 offset:0x3e00
	s_waitcnt vmcnt(0) lgkmcnt(0)
	v_mfma_f32_32x32x16_bf16 v[18:33], v[66:69], v[74:77], v[18:33]
	s_barrier
	v_mfma_f32_32x32x16_bf16 v[2:17], v[66:69], v[82:85], v[2:17]
	v_mfma_f32_32x32x16_bf16 v[18:33], v[70:73], v[78:81], v[18:33]
	v_mfma_f32_32x32x16_bf16 v[2:17], v[70:73], v[86:89], v[2:17]
	s_cbranch_vccnz .LBB0_533
	s_mov_b32 m0, s82
	s_nop 0
	global_load_lds_dwordx4 v152, s[18:19]
	s_mov_b32 m0, s83
	s_nop 0
	global_load_lds_dwordx4 v153, s[18:19]
	s_add_u32 s18, s18, 0x18000
	s_addc_u32 s19, s19, 0
.LBB0_533:
	ds_read_b128 v[66:69], v187 offset:49152
	ds_read_b128 v[70:73], v188 offset:49152
	ds_read_b128 v[74:77], v189 offset:49152
	ds_read_b128 v[78:81], v190 offset:49152
	v_mfma_f32_32x32x16_bf16 v[82:97], v[250:253], v[252:255], 0
	s_waitcnt lgkmcnt(3)
	v_mfma_f32_32x32x16_bf16 v[82:97], v[66:69], v[98:101], v[82:97]
	ds_read_b128 v[66:69], v191 offset:49152
	s_waitcnt lgkmcnt(3)
	v_mfma_f32_32x32x16_bf16 v[82:97], v[70:73], v[102:105], v[82:97]
	ds_read_b128 v[70:73], v192 offset:49152
	s_waitcnt lgkmcnt(3)
	v_mfma_f32_32x32x16_bf16 v[82:97], v[74:77], v[106:109], v[82:97]
	ds_read_b128 v[74:77], v193 offset:49152
	s_waitcnt lgkmcnt(3)
	v_mfma_f32_32x32x16_bf16 v[82:97], v[78:81], v[110:113], v[82:97]
	ds_read_b128 v[78:81], v194 offset:49152
	s_waitcnt lgkmcnt(3)
	v_mfma_f32_32x32x16_bf16 v[82:97], v[66:69], v[114:117], v[82:97]
	ds_read_b128 v[66:69], v157 offset:8192
	s_waitcnt lgkmcnt(3)
	v_mfma_f32_32x32x16_bf16 v[82:97], v[70:73], v[118:121], v[82:97]
	ds_read_b128 v[70:73], v158 offset:8192
	s_waitcnt lgkmcnt(3)
	v_mfma_f32_32x32x16_bf16 v[82:97], v[74:77], v[122:125], v[82:97]
	ds_read_b128 v[74:77], v159 offset:8192
	s_waitcnt lgkmcnt(3)
	v_mfma_f32_32x32x16_bf16 v[82:97], v[78:81], v[126:129], v[82:97]
	ds_read_b128 v[78:81], v160 offset:8192
	s_waitcnt lgkmcnt(3)
	v_mfma_f32_32x32x16_bf16 v[82:97], v[66:69], v[130:133], v[82:97]
	ds_read_b128 v[66:69], v187 offset:57344
	ds_read_b128 v[204:207], v188 offset:57344
	s_waitcnt lgkmcnt(4)
	v_mfma_f32_32x32x16_bf16 v[82:97], v[70:73], v[134:137], v[82:97]
	ds_read_b128 v[208:211], v189 offset:57344
	ds_read_b128 v[212:215], v190 offset:57344
	s_waitcnt lgkmcnt(5)
	v_mfma_f32_32x32x16_bf16 v[82:97], v[74:77], v[138:141], v[82:97]
	ds_read_b128 v[216:219], v191 offset:57344
	ds_read_b128 v[220:223], v192 offset:57344
	s_waitcnt lgkmcnt(6)
	v_mfma_f32_32x32x16_bf16 v[82:97], v[78:81], v[142:145], v[82:97]
	ds_read_b128 v[224:227], v193 offset:57344
	ds_read_b128 v[228:231], v194 offset:57344
	s_nop 3
	s_waitcnt lgkmcnt(2)
	v_mfma_f32_32x32x16_bf16 v[66:81], v[66:69], v[98:101], 0
	ds_read_b128 v[232:235], v157 offset:12288
	ds_read_b128 v[236:239], v158 offset:12288
	ds_read_b128 v[240:243], v159 offset:12288
	ds_read_b128 v[244:247], v160 offset:12288
	v_max_f32_e32 v162, v82, v83
	v_max3_f32 v166, v85, v86, v87
	v_max3_f32 v162, v162, v84, v88
	v_max3_f32 v163, v166, v90, v91
	v_mfma_f32_32x32x16_bf16 v[66:81], v[204:207], v[102:105], v[66:81]
	v_max3_f32 v162, v162, v89, v92
	v_max3_f32 v163, v163, v94, v95
	v_max3_f32 v162, v162, v93, v96
	v_max3_f32 v162, v162, v97, v163
	v_mov_b32_e32 v163, v162
	s_nop 1
	v_permlane32_swap_b32_e32 v162, v163
	v_mfma_f32_32x32x16_bf16 v[66:81], v[208:211], v[106:109], v[66:81]
	v_max_f32_e32 v162, v162, v163
	v_cmp_ge_f32_e32 vcc, s99, v162
	s_cmp_eq_u64 vcc, exec
	s_cbranch_scc0 .Lrare_10
	v_mov_b32_e32 v249, 1.0
; __device__ __forceinline__ void sm_half(f32x16& p, float& m_reg, float& l_reg, float& alpha, bf16x8& paL, bf16x8& paH) {
;   float a = fmaxf(fmaxf(p[0], p[1]), p[2]), b = fmaxf(fmaxf(p[3], p[4]), p[5]);
;   a = fmaxf(fmaxf(a, p[6]), p[7]); b = fmaxf(fmaxf(b, p[8]), p[9]); a = fmaxf(fmaxf(a, p[10]), p[11]); b = fmaxf(fmaxf(b, p[12]), p[13]); a = fmaxf(fmaxf(a, p[14]), p[15]);
;   float pmax = fmaxf(a, b);
;   { auto rr = __builtin_amdgcn_permlane32_swap(__float_as_uint(pmax), __float_as_uint(pmax), false, false);
;     pmax = fmaxf(__uint_as_float(rr[0]), __uint_as_float(rr[1])); }
;   const bool keep = __all(pmax - m_reg <= THRL);
;   const float mn = keep ? m_reg : fmaxf(m_reg, pmax);
;   alpha = __builtin_amdgcn_exp2f(m_reg - mn); m_reg = mn;
; #pragma unroll
;   for (int r = 0; r < 16; ++r) p[r] = __builtin_amdgcn_exp2f(p[r] - mn);
;   float ps = 0;
; #pragma unroll
;   for (int r = 0; r < 16; ++r) ps += p[r];
;   { auto rr = __builtin_amdgcn_permlane32_swap(__float_as_uint(ps), __float_as_uint(ps), false, false);
;     ps = __uint_as_float(rr[0]) + __uint_as_float(rr[1]); }
;   l_reg = l_reg * alpha + ps;
;     ...
;   PK4(p, 0, paL); PK4(p, 8, paH);
;     ...
; }
; template <int H> __device__ __forceinline__ void qkt_half(f32x16& p, const char* Kn, const char* Kr, const bf16x8* qr, int r32, int hi) {
;   p = f32x16{};
; #pragma unroll
;   for (int d0 = 0; d0 < 8; ++d0) { const int cb = (d0 * 16 + hi * 8) * 2;
;     const bf16x8 f = *reinterpret_cast<const bf16x8*>(Kn + KSWZ(32 * H + r32, cb)); p = __builtin_amdgcn_mfma_f32_32x32x16_bf16(f, qr[d0], p, 0, 0, 0); }
; #pragma unroll
;   for (int d0 = 0; d0 < 4; ++d0) { const int cb = (d0 * 16 + hi * 8) * 2;
;     const bf16x8 f = *reinterpret_cast<const bf16x8*>(Kr + KRSWZ(32 * H + r32, cb)); p = __builtin_amdgcn_mfma_f32_32x32x16_bf16(f, qr[8 + d0], p, 0, 0, 0); }
; }
.Lcont_10:
	v_mfma_f32_32x32x16_bf16 v[66:81], v[212:215], v[110:113], v[66:81]
	v_exp_f32_e32 v82, v82
	v_mfma_f32_32x32x16_bf16 v[66:81], v[216:219], v[114:117], v[66:81]
	v_exp_f32_e32 v83, v83
	v_exp_f32_e32 v84, v84
	v_mfma_f32_32x32x16_bf16 v[66:81], v[220:223], v[118:121], v[66:81]
	v_exp_f32_e32 v85, v85
	v_exp_f32_e32 v86, v86
	v_exp_f32_e32 v163, v90
	v_exp_f32_e32 v166, v91
	s_waitcnt lgkmcnt(4)
	v_mfma_f32_32x32x16_bf16 v[66:81], v[224:227], v[122:125], v[66:81]
	v_exp_f32_e32 v87, v87
	v_add_f32_e32 v91, v83, v82
	v_exp_f32_e32 v88, v88
	v_add_f32_e32 v91, v84, v91
	v_exp_f32_e32 v89, v89
	v_mfma_f32_32x32x16_bf16 v[66:81], v[228:231], v[126:129], v[66:81]
	v_add_f32_e32 v91, v85, v91
	v_add_f32_e32 v91, v86, v91
	v_add_f32_e32 v91, v87, v91
	v_exp_f32_e32 v167, v92
	v_add_f32_e32 v91, v88, v91
	s_waitcnt lgkmcnt(0)
	v_mfma_f32_32x32x16_bf16 v[66:81], v[232:235], v[130:133], v[66:81]
	v_exp_f32_e32 v93, v93
	v_add_f32_e32 v91, v89, v91
	v_exp_f32_e32 v94, v94
	v_add_f32_e32 v91, v163, v91
	v_mfma_f32_32x32x16_bf16 v[66:81], v[236:239], v[134:137], v[66:81]
	v_exp_f32_e32 v95, v95
	v_add_f32_e32 v91, v166, v91
	v_exp_f32_e32 v96, v96
	v_add_f32_e32 v91, v167, v91
	v_exp_f32_e32 v97, v97
	v_add_f32_e32 v91, v93, v91
	v_mfma_f32_32x32x16_bf16 v[66:81], v[240:243], v[138:141], v[66:81]
	v_add_f32_e32 v91, v94, v91
	v_add_f32_e32 v91, v95, v91
	v_add_f32_e32 v91, v96, v91
	v_add_f32_e32 v91, v97, v91
	v_cvt_pk_bf16_f32 v82, v82, v83
	v_cvt_pk_bf16_f32 v83, v84, v85
	v_mfma_f32_32x32x16_bf16 v[66:81], v[244:247], v[142:145], v[66:81]
	v_mfma_f32_32x32x16_bf16 v[66:81], v[250:253], v[252:255], v[66:81]
	v_cvt_pk_bf16_f32 v84, v86, v87
	v_cvt_pk_bf16_f32 v85, v88, v89
	v_cvt_pk_bf16_f32 v86, v163, v166
	v_cvt_pk_bf16_f32 v87, v167, v93
	v_cvt_pk_bf16_f32 v88, v94, v95
	v_cvt_pk_bf16_f32 v89, v96, v97
	s_nop 0
	v_permlane32_swap_b32_e32 v82, v84
	v_permlane32_swap_b32_e32 v83, v85
	v_permlane32_swap_b32_e32 v86, v88
	v_permlane32_swap_b32_e32 v87, v89
	s_cbranch_scc1 .LBB0_537
	s_and_saveexec_b64 s[66:67], s[0:1]
	ds_write_b32 v196, v249 offset:128
	s_or_b64 exec, exec, s[66:67]
	s_waitcnt lgkmcnt(0)
	v_add_u32_e32 v93, s80, v176
	ds_read_b128 v[94:97], v93 offset:224
	ds_read_b128 v[204:207], v93 offset:192
	ds_read_b128 v[208:211], v93 offset:160
	ds_read_b128 v[212:215], v93 offset:128
	s_waitcnt lgkmcnt(0)
	v_pk_mul_f32 v[62:63], v[62:63], v[94:95]
	v_pk_mul_f32 v[58:59], v[58:59], v[204:205]
	v_pk_mul_f32 v[54:55], v[54:55], v[208:209]
	v_pk_mul_f32 v[64:65], v[64:65], v[96:97]
	v_pk_mul_f32 v[60:61], v[60:61], v[206:207]
	v_pk_mul_f32 v[56:57], v[56:57], v[210:211]
	v_pk_mul_f32 v[52:53], v[52:53], v[214:215]
	v_pk_mul_f32 v[50:51], v[50:51], v[212:213]
	v_pk_mul_f32 v[46:47], v[46:47], v[94:95]
	v_pk_mul_f32 v[42:43], v[42:43], v[204:205]
	v_pk_mul_f32 v[38:39], v[38:39], v[208:209]
	v_pk_mul_f32 v[48:49], v[48:49], v[96:97]
	v_pk_mul_f32 v[44:45], v[44:45], v[206:207]
	v_pk_mul_f32 v[40:41], v[40:41], v[210:211]
	v_pk_mul_f32 v[36:37], v[36:37], v[214:215]
	v_pk_mul_f32 v[34:35], v[34:35], v[212:213]
	v_pk_mul_f32 v[30:31], v[30:31], v[94:95]
	v_pk_mul_f32 v[26:27], v[26:27], v[204:205]
	v_pk_mul_f32 v[22:23], v[22:23], v[208:209]
	v_pk_mul_f32 v[32:33], v[32:33], v[96:97]
	v_pk_mul_f32 v[28:29], v[28:29], v[206:207]
	v_pk_mul_f32 v[24:25], v[24:25], v[210:211]
	v_pk_mul_f32 v[20:21], v[20:21], v[214:215]
	v_pk_mul_f32 v[18:19], v[18:19], v[212:213]
	v_pk_mul_f32 v[14:15], v[14:15], v[94:95]
	v_pk_mul_f32 v[10:11], v[10:11], v[204:205]
	v_pk_mul_f32 v[6:7], v[6:7], v[208:209]
	v_pk_mul_f32 v[16:17], v[16:17], v[96:97]
	v_pk_mul_f32 v[12:13], v[12:13], v[206:207]
	v_pk_mul_f32 v[8:9], v[8:9], v[210:211]
	v_pk_mul_f32 v[4:5], v[4:5], v[214:215]
	v_pk_mul_f32 v[2:3], v[2:3], v[212:213]

; __device__ __forceinline__ void sm_half(f32x16& p, float& m_reg, float& l_reg, float& alpha, bf16x8& paL, bf16x8& paH) {
;   float a = fmaxf(fmaxf(p[0], p[1]), p[2]), b = fmaxf(fmaxf(p[3], p[4]), p[5]);
;   a = fmaxf(fmaxf(a, p[6]), p[7]); b = fmaxf(fmaxf(b, p[8]), p[9]); a = fmaxf(fmaxf(a, p[10]), p[11]); b = fmaxf(fmaxf(b, p[12]), p[13]); a = fmaxf(fmaxf(a, p[14]), p[15]);
;   float pmax = fmaxf(a, b);
;   { auto rr = __builtin_amdgcn_permlane32_swap(__float_as_uint(pmax), __float_as_uint(pmax), false, false);
;     pmax = fmaxf(__uint_as_float(rr[0]), __uint_as_float(rr[1])); }
;   const bool keep = __all(pmax - m_reg <= THRL);
;   const float mn = keep ? m_reg : fmaxf(m_reg, pmax);
;   alpha = __builtin_amdgcn_exp2f(m_reg - mn); m_reg = mn;
; #pragma unroll
;   for (int r = 0; r < 16; ++r) p[r] = __builtin_amdgcn_exp2f(p[r] - mn);
;   float ps = 0;
; #pragma unroll
;   for (int r = 0; r < 16; ++r) ps += p[r];
;   { auto rr = __builtin_amdgcn_permlane32_swap(__float_as_uint(ps), __float_as_uint(ps), false, false);
;     ps = __uint_as_float(rr[0]) + __uint_as_float(rr[1]); }
;   l_reg = l_reg * alpha + ps;
;     ...
;   PK4(p, 0, paL); PK4(p, 8, paH);
;     ...
; }
; template <int H> __device__ __forceinline__ void qkt_half(f32x16& p, const char* Kn, const char* Kr, const bf16x8* qr, int r32, int hi) {
;   p = f32x16{};
; #pragma unroll
;   for (int d0 = 0; d0 < 8; ++d0) { const int cb = (d0 * 16 + hi * 8) * 2;
;     const bf16x8 f = *reinterpret_cast<const bf16x8*>(Kn + KSWZ(32 * H + r32, cb)); p = __builtin_amdgcn_mfma_f32_32x32x16_bf16(f, qr[d0], p, 0, 0, 0); }
; #pragma unroll
;   for (int d0 = 0; d0 < 4; ++d0) { const int cb = (d0 * 16 + hi * 8) * 2;
;     const bf16x8 f = *reinterpret_cast<const bf16x8*>(Kr + KRSWZ(32 * H + r32, cb)); p = __builtin_amdgcn_mfma_f32_32x32x16_bf16(f, qr[8 + d0], p, 0, 0, 0); }
; }
; template <int H, int D0> __device__ __forceinline__ VFrag pv_rd(int vb) {
;   VFrag f; f.l0 = tr_read<v_rd_off(D0, 2 * H, 0)>(vb); f.h0 = tr_read<v_rd_off(D0, 2 * H, 1)>(vb); f.l1 = tr_read<v_rd_off(D0, 2 * H + 1, 0)>(vb); f.h1 = tr_read<v_rd_off(D0, 2 * H + 1, 1)>(vb); return f;
; }
; __device__ __forceinline__ void pv_mma(f32x16& od, VFrag& f, bf16x8 paL, bf16x8 paH) {
;     ...
;   od = __builtin_amdgcn_mfma_f32_32x32x16_bf16(paL, PK(f.l0, f.h0), od, 0, 0, 0);
;   od = __builtin_amdgcn_mfma_f32_32x32x16_bf16(paH, PK(f.l1, f.h1), od, 0, 0, 0);
;     ...
; }
.LBB0_539:
	ds_read_b64_tr_b16 v[94:95], v181 offset:0
	ds_read_b64_tr_b16 v[96:97], v181 offset:0x800
	ds_read_b64_tr_b16 v[164:165], v181 offset:0x1000
	ds_read_b64_tr_b16 v[166:167], v181 offset:0x1800
	ds_read_b64_tr_b16 v[168:169], v181 offset:0x200
	ds_read_b64_tr_b16 v[170:171], v181 offset:0xa00
	ds_read_b64_tr_b16 v[204:205], v181 offset:0x1200
	ds_read_b64_tr_b16 v[206:207], v181 offset:0x1a00
	s_nop 1
	s_waitcnt lgkmcnt(4)
	v_mfma_f32_32x32x16_bf16 v[50:65], v[82:85], v[94:97], v[50:65]
	ds_read_b64_tr_b16 v[94:95], v181 offset:0x400
	ds_read_b64_tr_b16 v[96:97], v181 offset:0xc00
	v_max_f32_e32 v93, v66, v67
	ds_read_b64_tr_b16 v[208:209], v181 offset:0x1400
	v_max3_f32 v163, v69, v70, v71
	v_max3_f32 v93, v93, v68, v72
	ds_read_b64_tr_b16 v[210:211], v181 offset:0x1c00
	v_max3_f32 v163, v163, v74, v75
	v_max3_f32 v93, v93, v73, v76
	s_waitcnt lgkmcnt(4)
	v_max3_f32 v163, v163, v78, v79
	v_max3_f32 v93, v93, v77, v80
	ds_read_b64_tr_b16 v[212:213], v181 offset:0x600
	v_max3_f32 v93, v93, v81, v163
	ds_read_b64_tr_b16 v[214:215], v181 offset:0xe00
	v_mov_b32_e32 v163, v93
	ds_read_b64_tr_b16 v[216:217], v181 offset:0x1600
	s_nop 1
	v_permlane32_swap_b32_e32 v93, v163
	ds_read_b64_tr_b16 v[218:219], v181 offset:0x1e00
	s_waitcnt lgkmcnt(4)
	v_max_f32_e32 v93, v93, v163
	v_mfma_f32_32x32x16_bf16 v[18:33], v[82:85], v[94:97], v[18:33]
	v_cmp_ge_f32_e32 vcc, s99, v93
	s_cmp_eq_u64 vcc, exec
	s_cbranch_scc0 .Lrare_11
	v_mov_b32_e32 v93, 1.0
.Lcont_11:
	s_waitcnt lgkmcnt(0)
	v_mfma_f32_32x32x16_bf16 v[50:65], v[86:89], v[164:167], v[50:65]
	v_exp_f32_e32 v66, v66
	v_exp_f32_e32 v67, v67
	v_mfma_f32_32x32x16_bf16 v[34:49], v[82:85], v[168:171], v[34:49]
	v_exp_f32_e32 v68, v68
	v_exp_f32_e32 v69, v69
	v_exp_f32_e32 v70, v70
	v_exp_f32_e32 v71, v71
	v_mfma_f32_32x32x16_bf16 v[2:17], v[82:85], v[212:215], v[2:17]
	v_exp_f32_e32 v82, v74
	v_exp_f32_e32 v83, v75
	v_exp_f32_e32 v76, v76
	v_exp_f32_e32 v77, v77
	v_exp_f32_e32 v78, v78
	v_exp_f32_e32 v79, v79
	v_exp_f32_e32 v80, v80
	v_exp_f32_e32 v81, v81
	v_add_f32_e32 v74, v67, v66
	v_exp_f32_e32 v72, v72
	v_add_f32_e32 v74, v68, v74
	v_exp_f32_e32 v73, v73
	v_add_f32_e32 v74, v69, v74
	v_add_f32_e32 v74, v70, v74
	v_add_f32_e32 v74, v71, v74
	v_add_f32_e32 v74, v72, v74
	v_add_f32_e32 v74, v73, v74
	v_add_f32_e32 v74, v82, v74
	v_add_f32_e32 v74, v83, v74
	v_mfma_f32_32x32x16_bf16 v[34:49], v[86:89], v[204:207], v[34:49]
	v_add_f32_e32 v74, v76, v74
	v_add_f32_e32 v74, v77, v74
	v_add_f32_e32 v74, v78, v74
	v_add_f32_e32 v74, v79, v74
	v_add_f32_e32 v74, v80, v74
	v_mfma_f32_32x32x16_bf16 v[18:33], v[86:89], v[208:211], v[18:33]
	v_add_f32_e32 v74, v81, v74
	v_cvt_pk_bf16_f32 v66, v66, v67
	v_cvt_pk_bf16_f32 v67, v68, v69
	v_cvt_pk_bf16_f32 v68, v70, v71
	v_cvt_pk_bf16_f32 v69, v72, v73
	v_cvt_pk_bf16_f32 v70, v82, v83
	v_mfma_f32_32x32x16_bf16 v[2:17], v[86:89], v[216:219], v[2:17]
	v_cvt_pk_bf16_f32 v71, v76, v77
	v_cvt_pk_bf16_f32 v72, v78, v79
	v_cvt_pk_bf16_f32 v73, v80, v81
	s_nop 0
	v_permlane32_swap_b32_e32 v66, v68
	v_permlane32_swap_b32_e32 v67, v69
	v_permlane32_swap_b32_e32 v70, v72
	v_permlane32_swap_b32_e32 v71, v73
	s_cbranch_scc1 .LBB0_518
	s_and_saveexec_b64 s[64:65], s[0:1]
	s_cbranch_execz .LBB0_517
	ds_write_b32 v196, v93 offset:128
	s_branch .LBB0_517
.Lrare_00:
	v_lshlrev_b32_e32 v165, 16, v254
	v_sub_f32_e32 v238, v0, v165
	v_max_f32_e32 v238, v238, v161
	v_cvt_pk_bf16_f32 v238, v238, v238
	s_nop 0
	v_and_b32_e32 v238, 0xffff0000, v238
	v_add_f32_e32 v165, v238, v165
	v_sub_f32_e32 v82, v82, v165
	v_sub_f32_e32 v83, v83, v165
	v_sub_f32_e32 v84, v84, v165
	v_sub_f32_e32 v85, v85, v165
	v_sub_f32_e32 v86, v86, v165
	v_sub_f32_e32 v87, v87, v165
	v_sub_f32_e32 v88, v88, v165
	v_sub_f32_e32 v89, v89, v165
	v_sub_f32_e32 v90, v90, v165
	v_sub_f32_e32 v91, v91, v165
	v_sub_f32_e32 v92, v92, v165
	v_sub_f32_e32 v93, v93, v165
	v_sub_f32_e32 v94, v94, v165
	v_sub_f32_e32 v95, v95, v165
	v_sub_f32_e32 v96, v96, v165
	v_sub_f32_e32 v97, v97, v165
	v_sub_f32_e32 v0, v161, v238
	v_exp_f32_e32 v0, v0
	v_mov_b32_e32 v161, v238
	v_xor_b32_e32 v238, 0x80000000, v238
	v_lshrrev_b32_e32 v254, 16, v238
	s_mov_b32 s99, 0x41380000
	s_branch .Lcont_00
.Lrare_01:
	v_lshlrev_b32_e32 v91, 16, v254
	v_sub_f32_e32 v203, v90, v91
	v_max_f32_e32 v203, v203, v161
	v_cvt_pk_bf16_f32 v203, v203, v203
	s_nop 0
	v_and_b32_e32 v203, 0xffff0000, v203
	v_add_f32_e32 v91, v203, v91
	v_sub_f32_e32 v66, v66, v91
	v_sub_f32_e32 v67, v67, v91
	v_sub_f32_e32 v68, v68, v91
	v_sub_f32_e32 v69, v69, v91
	v_sub_f32_e32 v70, v70, v91
	v_sub_f32_e32 v71, v71, v91
	v_sub_f32_e32 v72, v72, v91
	v_sub_f32_e32 v73, v73, v91
	v_sub_f32_e32 v74, v74, v91
	v_sub_f32_e32 v75, v75, v91
	v_sub_f32_e32 v76, v76, v91
	v_sub_f32_e32 v77, v77, v91
	v_sub_f32_e32 v78, v78, v91
	v_sub_f32_e32 v79, v79, v91
	v_sub_f32_e32 v80, v80, v91
	v_sub_f32_e32 v81, v81, v91
	v_sub_f32_e32 v200, v161, v203
	v_exp_f32_e32 v200, v200
	v_mov_b32_e32 v161, v203
	v_xor_b32_e32 v203, 0x80000000, v203
	v_lshrrev_b32_e32 v254, 16, v203
	s_mov_b32 s99, 0x41380000
	s_branch .Lcont_01
; __device__ __forceinline__ int crow(int r, int hi) { return (r & 3) + 8 * (r >> 2) + 4 * hi; }
; __device__ __forceinline__ unsigned cvtpk(float lo, float hi) { unsigned r; asm volatile("v_cvt_pk_bf16_f32 %0, %1, %2" : "=v"(r) : "v"(lo), "v"(hi)); return r; }
; __device__ __forceinline__ void sm_half(f32x16& p, float& m_reg, float& l_reg, float& alpha, bf16x8& paL, bf16x8& paH) {
;     ...
;   const bool keep = __all(pmax - m_reg <= THRL);
;   const float mn = keep ? m_reg : fmaxf(m_reg, pmax);
;   alpha = __builtin_amdgcn_exp2f(m_reg - mn); m_reg = mn;
; __device__ __forceinline__ void attn_unit(const bf16_t* __restrict__ Qb, const bf16_t* __restrict__ KNh, const bf16_t* __restrict__ KRs, const bf16_t* __restrict__ Vh,
;                                           bf16_t* __restrict__ Ob, float* __restrict__ ssa, int seq, char* lds) {
;     ...
;   if (hi == 0) li_l[r32] = l_reg; asm volatile("s_waitcnt lgkmcnt(0)" ::: "memory");
;   int zo = 0; asm volatile("" : "+v"(zo));
;   bf16_t* Ow = Ob + (long)(wid * QBLK) * LDO; float* ssw = ssa + wid * QBLK;
; #pragma unroll
;   for (int r = 0; r < 16; ++r) { const int orow = crow(r, hi) + zo; const float rl = __builtin_amdgcn_rcpf(li_l[orow]); float s = 0.f;
; #pragma unroll
;     for (int d0 = 0; d0 < 4; ++d0) { const float v = o[d0][r] * rl; s += v * v; Ow[(long)orow * LDO + d0 * 32 + r32] = (bf16_t)(cvtpk(v, v) & 0xffffu); }
;     s += __shfl_xor(s, 1); s += __shfl_xor(s, 2); s += __shfl_xor(s, 4); s += __shfl_xor(s, 8); s += __shfl_xor(s, 16);
;     if (r32 == 0) atomicAdd(ssw + orow, s); }
.Lrare_10:
	v_lshlrev_b32_e32 v163, 16, v254
	v_sub_f32_e32 v166, v162, v163
	v_max_f32_e32 v166, v166, v161
	v_cvt_pk_bf16_f32 v166, v166, v166
	s_nop 0
	v_and_b32_e32 v166, 0xffff0000, v166
	v_add_f32_e32 v163, v166, v163
	v_sub_f32_e32 v82, v82, v163
	v_sub_f32_e32 v83, v83, v163
	v_sub_f32_e32 v84, v84, v163
	v_sub_f32_e32 v85, v85, v163
	v_sub_f32_e32 v86, v86, v163
	v_sub_f32_e32 v87, v87, v163
	v_sub_f32_e32 v88, v88, v163
	v_sub_f32_e32 v89, v89, v163
	v_sub_f32_e32 v90, v90, v163
	v_sub_f32_e32 v91, v91, v163
	v_sub_f32_e32 v92, v92, v163
	v_sub_f32_e32 v93, v93, v163
	v_sub_f32_e32 v94, v94, v163
	v_sub_f32_e32 v95, v95, v163
	v_sub_f32_e32 v96, v96, v163
	v_sub_f32_e32 v97, v97, v163
	v_sub_f32_e32 v249, v161, v166
	v_exp_f32_e32 v249, v249
	v_mov_b32_e32 v161, v166
	v_xor_b32_e32 v166, 0x80000000, v166
	v_lshrrev_b32_e32 v254, 16, v166
	s_mov_b32 s99, 0x41380000
	s_branch .Lcont_10
.Lrare_11:
	v_lshlrev_b32_e32 v94, 16, v254
	v_sub_f32_e32 v163, v93, v94
	v_max_f32_e32 v163, v163, v161
	v_cvt_pk_bf16_f32 v163, v163, v163
	s_nop 0
	v_and_b32_e32 v163, 0xffff0000, v163
	v_add_f32_e32 v94, v163, v94
	v_sub_f32_e32 v66, v66, v94
	v_sub_f32_e32 v67, v67, v94
	v_sub_f32_e32 v68, v68, v94
	v_sub_f32_e32 v69, v69, v94
	v_sub_f32_e32 v70, v70, v94
	v_sub_f32_e32 v71, v71, v94
	v_sub_f32_e32 v72, v72, v94
	v_sub_f32_e32 v73, v73, v94
	v_sub_f32_e32 v74, v74, v94
	v_sub_f32_e32 v75, v75, v94
	v_sub_f32_e32 v76, v76, v94
	v_sub_f32_e32 v77, v77, v94
	v_sub_f32_e32 v78, v78, v94
	v_sub_f32_e32 v79, v79, v94
	v_sub_f32_e32 v80, v80, v94
	v_sub_f32_e32 v81, v81, v94
	v_sub_f32_e32 v93, v161, v163
	v_exp_f32_e32 v93, v93
	v_mov_b32_e32 v161, v163
	v_xor_b32_e32 v163, 0x80000000, v163
	v_lshrrev_b32_e32 v254, 16, v163
	s_mov_b32 s99, 0x41380000
	s_branch .Lcont_11
.LBB0_542:
	v_mov_b32_e32 v198, v197
	s_nop 1
	v_permlane32_swap_b32_e32 v197, v198
	v_add_f32_e32 v197, v197, v198
	s_and_saveexec_b64 s[62:63], s[0:1]
	ds_write_b32 v196, v197
	s_or_b64 exec, exec, s[62:63]
	v_mov_b32_e32 v0, 0
	s_waitcnt lgkmcnt(0)
	s_lshl_b64 s[62:63], s[58:59], 11
	v_add_u32_e32 v66, v0, v182
	v_lshl_add_u32 v72, v66, 2, s80
	ds_read_b32 v0, v72
	s_add_u32 s62, s24, s62
	s_addc_u32 s63, s25, s63
	s_add_u32 s60, s62, s60
	s_addc_u32 s61, s63, s61
	s_waitcnt lgkmcnt(0)
	v_rcp_f32_e32 v0, v0
	s_lshl_b64 s[58:59], s[58:59], 2
	s_add_u32 s62, s31, s58
	s_addc_u32 s63, s33, s59
	v_mul_f32_e32 v73, v34, v0
	v_mul_f32_e32 v75, v2, v0
	v_and_b32_e32 v2, 64, v195
	v_mul_f32_e32 v50, v50, v0
	v_mul_f32_e32 v34, v73, v73
	v_mul_f32_e32 v74, v18, v0
	v_xor_b32_e32 v0, 1, v195
	v_add_u32_e32 v76, 64, v2
	v_fmac_f32_e32 v34, v50, v50
	v_cmp_lt_i32_e32 vcc, v0, v76
	v_fmac_f32_e32 v34, v74, v74
	v_fmac_f32_e32 v34, v75, v75
	v_cndmask_b32_e32 v0, v195, v0, vcc
	v_lshlrev_b32_e32 v2, 2, v0
	ds_bpermute_b32 v0, v2, v34
	s_lshl_b64 s[58:59], s[16:17], 11
	s_add_u32 s58, s60, s58
	s_addc_u32 s59, s61, s59
	v_cvt_pk_bf16_f32 v50, v50, v50
	s_waitcnt lgkmcnt(0)
	v_add_f32_e32 v34, v34, v0
	v_xor_b32_e32 v0, 2, v195
	v_cmp_lt_i32_e32 vcc, v0, v76
	s_lshl_b64 s[60:61], s[16:17], 2
	s_add_u32 s60, s62, s60
	v_cndmask_b32_e32 v0, v195, v0, vcc
	v_lshlrev_b32_e32 v18, 2, v0
	ds_bpermute_b32 v67, v18, v34
	v_lshlrev_b32_e32 v0, 1, v148
	v_lshl_add_u64 v[68:69], s[58:59], 0, v[0:1]
	v_xor_b32_e32 v0, 4, v195
	v_cmp_lt_i32_e32 vcc, v0, v76
	s_waitcnt lgkmcnt(0)
	v_add_f32_e32 v34, v34, v67
	v_ashrrev_i32_e32 v67, 31, v66
	v_cndmask_b32_e32 v0, v195, v0, vcc
	v_lshlrev_b32_e32 v0, 2, v0
	ds_bpermute_b32 v77, v0, v34
	v_lshl_add_u64 v[68:69], v[68:69], 0, s[52:53]
	v_lshlrev_b64 v[70:71], 11, v[66:67]
	v_lshl_add_u64 v[70:71], v[68:69], 0, v[70:71]
	global_store_short v[70:71], v50, off
	s_waitcnt lgkmcnt(0)
	v_add_f32_e32 v77, v34, v77
	v_xor_b32_e32 v34, 8, v195
	v_cmp_lt_i32_e32 vcc, v34, v76
	v_cvt_pk_bf16_f32 v50, v73, v73
	global_store_short v[70:71], v50, off offset:64
	v_xor_b32_e32 v50, 16, v195
	v_cndmask_b32_e32 v34, v195, v34, vcc
	v_lshlrev_b32_e32 v34, 2, v34
	ds_bpermute_b32 v78, v34, v77
	v_cmp_lt_i32_e32 vcc, v50, v76
	v_cvt_pk_bf16_f32 v79, v74, v74
	s_addc_u32 s61, s63, s61
	global_store_short v[70:71], v79, off offset:128
	v_cndmask_b32_e32 v50, v195, v50, vcc
	s_waitcnt lgkmcnt(0)
	v_add_f32_e32 v73, v77, v78
	v_lshlrev_b32_e32 v50, 2, v50
	ds_bpermute_b32 v74, v50, v73
	v_cvt_pk_bf16_f32 v75, v75, v75
	global_store_short v[70:71], v75, off offset:192
	v_lshl_add_u64 v[70:71], v[66:67], 2, s[60:61]
	s_and_saveexec_b64 s[58:59], s[2:3]
	s_cbranch_execz .LBB0_546
	s_waitcnt lgkmcnt(0)
	v_add_f32_e32 v67, v73, v74
	global_atomic_add_f32 v[70:71], v67, off

; #define LAS __attribute__((address_space(3)))
; __global__ void __launch_bounds__(NTHREADS, 2) enc_fwd(Params a) {
;     extern __shared__ __attribute__((aligned(16))) unsigned char lds_raw[];
;     LAS unsigned char* lds = (LAS unsigned char*)lds_raw;
;     const int lo = a.ph_lo, hi = a.ph_hi, G = gridDim.x;
	.amdhsa_kernel _Z7enc_fwd6Params
		.amdhsa_group_segment_fixed_size 0
		.amdhsa_private_segment_fixed_size 0
		.amdhsa_kernarg_size 464
		.amdhsa_user_sgpr_count 2
		.amdhsa_user_sgpr_dispatch_ptr 0
		.amdhsa_user_sgpr_queue_ptr 0
		.amdhsa_user_sgpr_kernarg_segment_ptr 1
		.amdhsa_user_sgpr_dispatch_id 0
		.amdhsa_user_sgpr_kernarg_preload_length 0
		.amdhsa_user_sgpr_kernarg_preload_offset 0
		.amdhsa_user_sgpr_private_segment_size 0
		.amdhsa_uses_dynamic_stack 0
		.amdhsa_enable_private_segment 0
		.amdhsa_system_sgpr_workgroup_id_x 1
		.amdhsa_system_sgpr_workgroup_id_y 0
		.amdhsa_system_sgpr_workgroup_id_z 0
		.amdhsa_system_sgpr_workgroup_info 0
		.amdhsa_system_vgpr_workitem_id 2
		.amdhsa_next_free_vgpr 256
		.amdhsa_next_free_sgpr 100
		.amdhsa_accum_offset 256
		.amdhsa_reserve_vcc 1
		.amdhsa_float_round_mode_32 0
		.amdhsa_float_round_mode_16_64 0
		.amdhsa_float_denorm_mode_32 3
		.amdhsa_float_denorm_mode_16_64 3
		.amdhsa_dx10_clamp 1
		.amdhsa_ieee_mode 1
		.amdhsa_fp16_overflow 0
		.amdhsa_tg_split 0
		.amdhsa_exception_fp_ieee_invalid_op 0
		.amdhsa_exception_fp_denorm_src 0
		.amdhsa_exception_fp_ieee_div_zero 0
		.amdhsa_exception_fp_ieee_overflow 0
		.amdhsa_exception_fp_ieee_underflow 0
		.amdhsa_exception_fp_ieee_inexact 0
		.amdhsa_exception_int_div_zero 0
	.end_amdhsa_kernel

; #define LAS __attribute__((address_space(3)))
; __global__ void __launch_bounds__(NTHREADS, 2) enc_fwd(Params a) {
;     extern __shared__ __attribute__((aligned(16))) unsigned char lds_raw[];
;     LAS unsigned char* lds = (LAS unsigned char*)lds_raw;
;     const int lo = a.ph_lo, hi = a.ph_hi, G = gridDim.x;
.Lfunc_end0:
	.size	_Z7enc_fwd6Params, .Lfunc_end0-_Z7enc_fwd6Params
	.set _Z7enc_fwd6Params.num_vgpr, 256
	.set _Z7enc_fwd6Params.num_agpr, 0
	.set _Z7enc_fwd6Params.numbered_sgpr, 100
	.set _Z7enc_fwd6Params.num_named_barrier, 0
	.set _Z7enc_fwd6Params.private_seg_size, 0
	.set _Z7enc_fwd6Params.uses_vcc, 1
	.set _Z7enc_fwd6Params.uses_flat_scratch, 0
	.set _Z7enc_fwd6Params.has_dyn_sized_stack, 0
	.set _Z7enc_fwd6Params.has_recursion, 0
	.set _Z7enc_fwd6Params.has_indirect_call, 0

; #define LAS __attribute__((address_space(3)))
; __global__ void __launch_bounds__(NTHREADS, 2) enc_fwd(Params a) {
;     extern __shared__ __attribute__((aligned(16))) unsigned char lds_raw[];
;     LAS unsigned char* lds = (LAS unsigned char*)lds_raw;
;     const int lo = a.ph_lo, hi = a.ph_hi, G = gridDim.x;
amdhsa.kernels:
  - .agpr_count:     0
    .args:
      - .offset:         0
        .size:           208
        .value_kind:     by_value
      - .offset:         208
        .size:           4
        .value_kind:     hidden_block_count_x
      - .offset:         212
        .size:           4
        .value_kind:     hidden_block_count_y
      - .offset:         216
        .size:           4
        .value_kind:     hidden_block_count_z
      - .offset:         220
        .size:           2
        .value_kind:     hidden_group_size_x
      - .offset:         222
        .size:           2
        .value_kind:     hidden_group_size_y
      - .offset:         224
        .size:           2
        .value_kind:     hidden_group_size_z
      - .offset:         226
        .size:           2
        .value_kind:     hidden_remainder_x
      - .offset:         228
        .size:           2
        .value_kind:     hidden_remainder_y
      - .offset:         230
        .size:           2
        .value_kind:     hidden_remainder_z
      - .offset:         248
        .size:           8
        .value_kind:     hidden_global_offset_x
      - .offset:         256
        .size:           8
        .value_kind:     hidden_global_offset_y
      - .offset:         264
        .size:           8
        .value_kind:     hidden_global_offset_z
      - .offset:         272
        .size:           2
        .value_kind:     hidden_grid_dims
      - .offset:         296
        .size:           8
        .value_kind:     hidden_multigrid_sync_arg
      - .offset:         328
        .size:           4
        .value_kind:     hidden_dynamic_lds_size
    .group_segment_fixed_size: 0
    .kernarg_segment_align: 8
    .kernarg_segment_size: 464
    .language:       OpenCL C
    .language_version:
      - 2
      - 0
    .max_flat_workgroup_size: 512
    .name:           _Z7enc_fwd6Params
    .private_segment_fixed_size: 0
    .sgpr_count:     106
    .sgpr_spill_count: 54
    .symbol:         _Z7enc_fwd6Params.kd
    .uniform_work_group_size: 1
    .uses_dynamic_stack: false
    .vgpr_count:     256
    .vgpr_spill_count: 0
    .wavefront_size: 64
